# MLA loop: one barrier per tile (V quad-buffered in LDS), staging writes late, incremental K pointers, fp8 packs behind last QK MFMA, split max chain
# speedup vs baseline: 1.0150x; 1.0148x over previous
; #define SWAIT() do { if constexpr (SD == 1) asm volatile("s_waitcnt vmcnt(0)" ::: "memory"); else if constexpr (MODE == 0) asm volatile("s_waitcnt vmcnt(5)" ::: "memory"); else asm volatile("s_waitcnt vmcnt(4)" ::: "memory"); } while (0)
; template <int MODE>
; __device__ __forceinline__ void partialSM(f32x16& p0, f32x16& p1, float& m_reg, float& mn, float& alpha, const float C, int kb, const float* btab, const bool nomask) {
;     ...
;     { const bool keep = __all((pmax - m_reg) * C <= (MODE == 0 ? 7.5f : 11.5f)); mn = keep ? m_reg : fmaxf(m_reg, pmax);   alpha = __builtin_amdgcn_exp2f((m_reg - mn) * C); m_reg = mn; }
;     const float mnC = -mn * C;
; #pragma unroll
;     for (int r = 0; r < 16; ++r) p0[r] = fmaf(p0[r], C, mnC);
; #pragma unroll
;     for (int r = 0; r < 16; ++r) p1[r] = fmaf(p1[r], C, mnC);
; #pragma unroll
;     for (int r = 0; r < 16; ++r) p0[r] = __builtin_amdgcn_exp2f(p0[r]);
; template <int MODE, int SD> ...
;     ...
;   f32x16 pA0, pA1, pB0, pB1; float mnA, mnB, alA, alB; bf16x8 pa0, pa1, pa2 = {}, pa3 = {};
;   const int kbl = kbw - wid * QBLK - r32 + 4 * hi;
;   constexpr int SE = 0, SO = SD - 1;
;   SLOAD(SE, 0); asm volatile("s_waitcnt vmcnt(0)" ::: "memory"); SWRITE(0, SE); __syncthreads();
;   qkt<MODE>(pA0, pA1, K_lds, Kr_lds, Qr_l, qr, q8, r32, hi); partialSM<MODE>(pA0, pA1, m_reg, mnA, alA, C, kbl, btab, nomask);
;   SLOAD(SO, KVBLK); if constexpr (SD == 2) { if (2 < NT) SLOAD(SE, 2 * KVBLK); }
;   SWAIT(); SWRITE(1, SO); __syncthreads();
;   for (int j = 1; j + 1 < NT; j += 2) {
.LBB0_648:
	s_or_b64 exec, exec, s[20:21]
	v_max_f32_e32 v42, 0xf149f2ca, v46
	v_cndmask_b32_e64 v237, v222, v42, s[14:15]
	v_mul_f32_e32 v42, 0xbdd53b94, v237
	v_fmamk_f32 v18, v18, 0x3dd53b94, v42
	v_fmamk_f32 v19, v19, 0x3dd53b94, v42
	v_fmamk_f32 v20, v20, 0x3dd53b94, v42
	v_fmamk_f32 v21, v21, 0x3dd53b94, v42
	v_fmamk_f32 v22, v22, 0x3dd53b94, v42
	v_fmamk_f32 v23, v23, 0x3dd53b94, v42
	v_fmamk_f32 v24, v24, 0x3dd53b94, v42
	v_fmamk_f32 v25, v25, 0x3dd53b94, v42
	v_fmamk_f32 v26, v26, 0x3dd53b94, v42
	v_fmamk_f32 v27, v27, 0x3dd53b94, v42
	v_fmamk_f32 v28, v28, 0x3dd53b94, v42
	v_fmamk_f32 v29, v29, 0x3dd53b94, v42
	v_fmamk_f32 v30, v30, 0x3dd53b94, v42
	v_fmamk_f32 v31, v31, 0x3dd53b94, v42
	v_fmamk_f32 v32, v32, 0x3dd53b94, v42
	v_fmamk_f32 v33, v33, 0x3dd53b94, v42
	v_exp_f32_e32 v66, v18
	v_exp_f32_e32 v67, v19
	v_exp_f32_e32 v68, v20
	v_exp_f32_e32 v69, v21
	v_exp_f32_e32 v70, v22
	v_exp_f32_e32 v71, v23
	v_exp_f32_e32 v72, v24
	v_exp_f32_e32 v73, v25
	v_exp_f32_e32 v74, v26
	v_exp_f32_e32 v75, v27
	v_exp_f32_e32 v76, v28
	v_exp_f32_e32 v77, v29
	v_exp_f32_e32 v78, v30
	v_exp_f32_e32 v79, v31
	v_exp_f32_e32 v80, v32
	v_exp_f32_e32 v81, v33
	s_waitcnt vmcnt(0)
	v_mul_u32_u24_e32 v18, 0xd0, v223
	s_waitcnt vmcnt(1)
	ds_write_b128 v225, v[34:37] offset:18432
	s_waitcnt vmcnt(0)
	ds_write_b128 v226, v[38:41] offset:49152
	s_and_saveexec_b64 s[14:15], vcc
	s_xor_b64 s[14:15], exec, s[14:15]
	v_lshlrev_b32_e32 v154, 4, v156
	v_mul_lo_u32 v177, v155, s90
	s_andn2_saveexec_b64 s[14:15], s[14:15]
	v_add3_u32 v19, 0, v177, v154
	ds_write_b128 v19, v[178:181] offset:49152
	s_or_b64 exec, exec, s[14:15]
	v_pk_fma_f32 v[98:99], v[2:3], s[78:79], v[42:43] op_sel_hi:[1,0,0]
	v_and_b32_e32 v2, 0x3fffffc0, v146
	v_pk_fma_f32 v[100:101], v[4:5], s[78:79], v[42:43] op_sel_hi:[1,0,0]
	v_lshl_add_u32 v4, v2, 2, s91
	v_lshrrev_b32_e32 v2, 3, v146
	v_and_b32_e32 v227, 4, v2
	v_mov_b32_e32 v2, v152
	v_mov_b32_e32 v3, v1
	v_lshl_add_u64 v[200:201], v[150:151], 0, v[2:3]
	v_add_u32_e32 v2, 0xffffff80, v154
	v_lshl_add_u64 v[202:203], v[150:151], 0, v[2:3]
	v_ashrrev_i32_e32 v155, 31, v154
	v_add_u32_e32 v2, v157, v174
	v_pk_fma_f32 v[106:107], v[10:11], s[78:79], v[42:43] op_sel_hi:[1,0,0]
	v_add3_u32 v10, v2, v176, v175
	v_lshl_add_u64 v[2:3], v[160:161], 0, v[154:155]
	v_lshl_add_u32 v229, v223, 2, v4
	v_lshl_add_u32 v228, v227, 2, v4
	v_mad_u64_u32 v[4:5], s[16:17], v10, s0, v[2:3]
	v_lshl_add_u64 v[204:205], s[84:85], 0, v[4:5]
	v_add_u32_e32 v4, v170, v171
	v_add3_u32 v11, v4, v173, v172
	v_lshl_add_u64 v[4:5], v[160:161], 0, v[152:153]
	v_pk_fma_f32 v[102:103], v[6:7], s[78:79], v[42:43] op_sel_hi:[1,0,0]
	v_mad_u64_u32 v[6:7], s[16:17], v11, s0, v[4:5]
	v_lshl_add_u64 v[206:207], s[84:85], 0, v[6:7]
	v_mad_u64_u32 v[6:7], s[16:17], v192, v147, v[148:149]
	v_lshlrev_b64 v[6:7], 7, v[6:7]
	v_pk_fma_f32 v[104:105], v[8:9], s[78:79], v[42:43] op_sel_hi:[1,0,0]
	v_lshl_add_u64 v[8:9], v[6:7], 0, v[158:159]
	s_nop 0
	v_lshl_add_u64 v[6:7], v[8:9], 0, v[0:1]
	v_add_u32_e32 v0, 0xc0, v10
	v_mul_u32_u24_e32 v0, 0xc00, v0
	v_sub_f32_e32 v19, 0xf149f2ca, v237
	v_lshl_add_u64 v[2:3], v[2:3], 0, v[0:1]
	v_add_u32_e32 v0, 0xc0, v11
	v_mul_f32_e32 v19, 0x3dd53b94, v19
	v_readlane_b32 s16, v255, 19
	v_mul_u32_u24_e32 v0, 0xc00, v0
	v_exp_f32_e32 v232, v19
	v_pk_fma_f32 v[112:113], v[16:17], s[78:79], v[42:43] op_sel_hi:[1,0,0]
	v_pk_fma_f32 v[110:111], v[14:15], s[78:79], v[42:43] op_sel_hi:[1,0,0]
	v_mul_u32_u24_e32 v16, 0x50, v223
	v_readlane_b32 s17, v255, 20
	v_lshl_add_u64 v[210:211], s[74:75], 0, v[2:3]
	v_lshl_add_u64 v[2:3], v[4:5], 0, v[0:1]
	v_mov_b32_e32 v14, v1
	v_mov_b32_e32 v15, v1
	v_pk_fma_f32 v[108:109], v[12:13], s[78:79], v[42:43] op_sel_hi:[1,0,0]
	v_add_u32_e32 v17, 0, v177
	v_lshl_add_u64 v[208:209], s[16:17], 0, v[6:7]
	v_lshl_add_u64 v[212:213], s[74:75], 0, v[2:3]
	v_mov_b32_e32 v0, v1
	v_mov_b32_e32 v2, v1
	v_mov_b32_e32 v3, v1
	v_mov_b32_e32 v4, v1
	v_mov_b32_e32 v5, v1
	v_mov_b32_e32 v6, v1
	v_mov_b32_e32 v7, v1
	v_mov_b32_e32 v8, v1
	v_mov_b32_e32 v9, v1
	v_mov_b32_e32 v10, v1
	v_mov_b32_e32 v11, v1
	v_mov_b32_e32 v12, v1
	v_mov_b32_e32 v13, v1
	v_add_u32_e32 v231, v50, v18
	v_add_u32_e32 v230, v50, v16
	v_mov_b64_e32 v[64:65], v[14:15]
	v_mov_b64_e32 v[48:49], v[14:15]
	v_mov_b64_e32 v[32:33], v[14:15]
	v_add_u32_e32 v234, v17, v154
	v_mov_b64_e32 v[62:63], v[12:13]
	v_mov_b64_e32 v[60:61], v[10:11]
	v_mov_b64_e32 v[58:59], v[8:9]
	v_mov_b64_e32 v[56:57], v[6:7]
	v_mov_b64_e32 v[54:55], v[4:5]
	v_mov_b64_e32 v[52:53], v[2:3]
	v_mov_b64_e32 v[50:51], v[0:1]
	v_mov_b64_e32 v[46:47], v[12:13]
	v_mov_b64_e32 v[44:45], v[10:11]
	v_mov_b64_e32 v[42:43], v[8:9]
	v_mov_b64_e32 v[40:41], v[6:7]
	v_mov_b64_e32 v[38:39], v[4:5]
	v_mov_b64_e32 v[36:37], v[2:3]
	v_mov_b64_e32 v[34:35], v[0:1]
	v_mov_b64_e32 v[30:31], v[12:13]
	v_mov_b64_e32 v[28:29], v[10:11]
	v_mov_b64_e32 v[26:27], v[8:9]
	v_mov_b64_e32 v[24:25], v[6:7]
	v_mov_b64_e32 v[22:23], v[4:5]
	v_mov_b64_e32 v[20:21], v[2:3]
	v_mov_b64_e32 v[18:19], v[0:1]
	v_mov_b64_e32 v[16:17], v[14:15]
	s_mov_b32 s24, 2
	v_lshrrev_b32_e32 v233, 6, v147
	v_cmp_lt_i32_e64 s[14:15], 7, v156
	v_mov_b32_e32 v193, 0
	s_mov_b32 s25, 1
	s_mov_b64 s[16:17], 0
	v_mov_b64_e32 v[14:15], v[12:13]
	v_mov_b64_e32 v[12:13], v[10:11]
	v_mov_b64_e32 v[10:11], v[8:9]
	v_mov_b64_e32 v[8:9], v[6:7]
	v_mov_b64_e32 v[6:7], v[4:5]
	v_mov_b64_e32 v[4:5], v[2:3]
	v_mov_b64_e32 v[2:3], v[0:1]
	s_lshl_b32 s26, s24, 6
	v_lshl_add_u64 v[206:207], v[206:207], 0, v[198:199]
	v_mov_b32_e32 v212, 0x30000
	v_mov_b32_e32 v213, 0
	s_and_saveexec_b64 s[20:21], s[10:11]
	v_or_b32_e32 v0, s26, v195
	v_lshlrev_b64 v[206:207], 6, v[0:1]
	v_lshl_add_u64 v[206:207], v[200:201], 0, v[206:207]
	v_lshl_add_u64 v[206:207], v[206:207], 0, s[92:93]
	v_mov_b32_e32 v212, 0x1000
	s_or_b64 exec, exec, s[20:21]
	v_lshl_add_u64 v[204:205], v[204:205], 0, v[198:199]
	v_mov_b32_e32 v210, 0x30000
	v_mov_b32_e32 v211, 0
	s_and_saveexec_b64 s[20:21], s[14:15]
	v_or_b32_e32 v0, s26, v224
	v_lshlrev_b64 v[204:205], 6, v[0:1]
	v_lshl_add_u64 v[204:205], v[202:203], 0, v[204:205]
	v_mov_b32_e32 v210, 0x1000
	s_or_b64 exec, exec, s[20:21]
	v_xor_b32_e32 v225, 0x10000, v225
	s_waitcnt lgkmcnt(0)
	s_barrier
	s_branch .LBB0_655

; template <int MODE>
; __device__ __forceinline__ void partialSM(f32x16& p0, f32x16& p1, float& m_reg, float& mn, float& alpha, const float C, int kb, const float* btab, const bool nomask) {
;     ...
;     float pmax = p0[0];
; #pragma unroll
;     for (int r = 1; r < 16; ++r) pmax = fmaxf(pmax, p0[r]);
; #pragma unroll
;     for (int r = 0; r < 16; ++r) pmax = fmaxf(pmax, p1[r]);
;     { auto rr = __builtin_amdgcn_permlane32_swap(__float_as_uint(pmax), __float_as_uint(pmax), false, false); pmax = fmaxf(__uint_as_float(rr[0]), __uint_as_float(rr[1])); }
;     { const bool keep = __all((pmax - m_reg) * C <= (MODE == 0 ? 7.5f : 11.5f)); mn = keep ? m_reg : fmaxf(m_reg, pmax);   alpha = __builtin_amdgcn_exp2f((m_reg - mn) * C); m_reg = mn; }
;     const float mnC = -mn * C;
; #pragma unroll
;     for (int r = 0; r < 16; ++r) p0[r] = fmaf(p0[r], C, mnC);
; #pragma unroll
;     for (int r = 0; r < 16; ++r) p1[r] = fmaf(p1[r], C, mnC);
; #pragma unroll
;     for (int r = 0; r < 16; ++r) p0[r] = __builtin_amdgcn_exp2f(p0[r]);
;   }
; }
; __device__ __forceinline__ void finishSM(f32x16& p0, f32x16& p1, float alpha, float& l_reg, bf16x8& pa0, bf16x8& pa1, bf16x8& pa2, bf16x8& pa3) {
; #pragma unroll
;   for (int r = 0; r < 16; ++r) p1[r] = __builtin_amdgcn_exp2f(p1[r]);
;   float ps = 0;
; #pragma unroll
;   for (int r = 0; r < 16; ++r) ps += p0[r];
; #pragma unroll
;   for (int r = 0; r < 16; ++r) ps += p1[r];
;   { auto rr = __builtin_amdgcn_permlane32_swap(__float_as_uint(ps), __float_as_uint(ps), false, false); ps = __uint_as_float(rr[0]) + __uint_as_float(rr[1]); }
;   l_reg = l_reg * alpha + ps;
;     ...
;   PK4(p0, 0, pa0); PK4(p0, 8, pa1); PK4(p1, 0, pa2); PK4(p1, 8, pa3);
;     ...
; }
; template <int MODE>
; __device__ __forceinline__ void qkt(f32x16& p0, f32x16& p1, const char* Ks, const char* Krs, const char* Qrs, const bf16x8* qr, const i32x8* q8, int r32, int hi) {
;   p0 = f32x16{}; p1 = f32x16{};
;   if constexpr (MODE == 0) {
; #pragma unroll
;     for (int kb = 0; kb < 3; ++kb) {
; #pragma unroll
;       for (int hf = 0; hf < 2; ++hf) { const char* a_ = Ks + (hf * 32 + r32) * 208 + kb * 64 + hi * 32;
;         const u32x4 lo = *reinterpret_cast<const u32x4*>(a_), h4 = *reinterpret_cast<const u32x4*>(a_ + 16);
;         const i32x8 a = {(int)lo.x, (int)lo.y, (int)lo.z, (int)lo.w, (int)h4.x, (int)h4.y, (int)h4.z, (int)h4.w};
.LBB0_654:
	s_waitcnt vmcnt(0)
	s_waitcnt vmcnt(1)
	ds_write_b128 v225, v[182:185] offset:18432
	s_waitcnt vmcnt(0)
	ds_write_b128 v226, v[186:189] offset:49152
	s_and_saveexec_b64 s[20:21], s[12:13]
	ds_write_b128 v234, v[178:181] offset:49152
	s_or_b64 exec, exec, s[20:21]
	v_add_f32_e32 v82, v235, v236
	s_add_i32 s24, s24, 2
	v_fmac_f32_e32 v82, v232, v193
	v_add_f32_e32 v193, v239, v240
	s_add_i32 s25, s25, 2
	s_mov_b64 s[20:21], 0x4000
	v_cmp_ge_u32_e32 vcc, s24, v233
	v_fmac_f32_e32 v193, v82, v0
	v_lshl_add_u64 v[208:209], v[208:209], 0, s[20:21]
	s_or_b64 s[16:17], vcc, s[16:17]
	v_mov_b32_e32 v232, v170
	v_xor_b32_e32 v230, 0x10000, v230
	v_xor_b32_e32 v225, 0x10000, v225
	s_waitcnt lgkmcnt(0)
	s_barrier
	s_andn2_b64 exec, exec, s[16:17]
	s_cbranch_execz .LBB0_686
.LBB0_655:
	ds_read_b128 v[82:85], v231 offset:49152
	ds_read_b128 v[86:89], v231 offset:49168
	ds_read_b128 v[122:125], v231 offset:49216
	ds_read_b128 v[126:129], v231 offset:49232
	ds_read_b128 v[162:165], v231 offset:49280
	ds_read_b128 v[166:169], v231 offset:49296
	ds_read_b128 v[146:149], v231 offset:55808
	ds_read_b128 v[150:153], v231 offset:55824
	ds_read_b128 v[154:157], v231 offset:55872
	ds_read_b128 v[158:161], v231 offset:55888
	ds_read_b128 v[170:173], v231 offset:55936
	ds_read_b128 v[174:177], v231 offset:55952
	global_load_dwordx4 v[182:185], v[208:209], off
	global_load_dwordx4 v[186:189], v[206:207], off
	s_and_saveexec_b64 s[20:21], s[12:13]
	global_load_dwordx4 v[178:181], v[204:205], off
	s_or_b64 exec, exec, s[20:21]
	v_lshl_add_u64 v[206:207], v[206:207], 0, v[212:213]
	v_lshl_add_u64 v[204:205], v[204:205], 0, v[210:211]
	s_waitcnt lgkmcnt(10)
	v_mfma_scale_f32_32x32x64_f8f6f4 v[82:97], v[82:89], v[114:121], 0, v216, v216 op_sel_hi:[0,0,0]
	v_exp_f32_e32 v240, v98
	v_exp_f32_e32 v242, v99
	v_exp_f32_e32 v239, v100
	v_exp_f32_e32 v241, v101
	v_exp_f32_e32 v245, v102
	v_exp_f32_e32 v246, v103
	v_add_f32_e32 v0, 0, v66
	v_add_f32_e32 v0, v67, v0
	s_waitcnt lgkmcnt(8)
	v_mfma_scale_f32_32x32x64_f8f6f4 v[82:97], v[122:129], v[130:137], v[82:97], v216, v216 op_sel_hi:[0,0,0]
	v_exp_f32_e32 v243, v104
	v_exp_f32_e32 v244, v105
	v_exp_f32_e32 v247, v106
	v_exp_f32_e32 v250, v107
	v_exp_f32_e32 v248, v108
	v_exp_f32_e32 v249, v109
	v_add_f32_e32 v0, v68, v0
	v_add_f32_e32 v0, v69, v0
	s_waitcnt lgkmcnt(6)
	v_mfma_scale_f32_32x32x64_f8f6f4 v[82:97], v[162:169], v[138:145], v[82:97], v216, v216 op_sel_hi:[0,0,0]
	v_exp_f32_e32 v191, v110
	v_exp_f32_e32 v217, v111
	v_exp_f32_e32 v251, v112
	v_exp_f32_e32 v252, v113
	v_add_f32_e32 v0, v70, v0
	v_add_f32_e32 v0, v71, v0
	v_add_f32_e32 v0, v72, v0
	v_add_f32_e32 v0, v73, v0
	v_add_f32_e32 v0, v74, v0
	v_add_f32_e32 v0, v75, v0
	s_waitcnt lgkmcnt(4)
	v_mfma_scale_f32_32x32x64_f8f6f4 v[98:113], v[146:153], v[114:121], 0, v216, v216 op_sel_hi:[0,0,0]
	v_add_f32_e32 v0, v76, v0
	v_add_f32_e32 v0, v77, v0
	v_add_f32_e32 v0, v78, v0
	v_add_f32_e32 v0, v79, v0
	v_add_f32_e32 v0, v80, v0
	v_add_f32_e32 v0, v81, v0
	v_add_f32_e32 v0, v240, v0
	v_add_f32_e32 v0, v242, v0
	v_add_f32_e32 v0, v239, v0
	v_add_f32_e32 v0, v241, v0
	v_add_f32_e32 v0, v245, v0
	s_waitcnt lgkmcnt(2)
	v_mfma_scale_f32_32x32x64_f8f6f4 v[98:113], v[154:161], v[130:137], v[98:113], v216, v216 op_sel_hi:[0,0,0]
	v_add_f32_e32 v0, v246, v0
	v_add_f32_e32 v0, v243, v0
	v_add_f32_e32 v0, v244, v0
	v_add_f32_e32 v0, v247, v0
	v_add_f32_e32 v0, v250, v0
	v_add_f32_e32 v0, v248, v0
	v_add_f32_e32 v0, v249, v0
	v_add_f32_e32 v0, v191, v0
	v_add_f32_e32 v0, v217, v0
	v_add_f32_e32 v0, v251, v0
	s_waitcnt lgkmcnt(0)
	v_mfma_scale_f32_32x32x64_f8f6f4 v[98:113], v[170:177], v[138:145], v[98:113], v216, v216 op_sel_hi:[0,0,0]
	s_nop 0
	v_add_f32_e32 v235, v252, v0
	v_mov_b32_e32 v236, v235
	s_nop 1
	v_permlane32_swap_b32_e32 v235, v236
	ds_read_b128 v[154:157], v230
	ds_read_b128 v[158:161], v230 offset:16
	ds_read_b128 v[146:149], v230 offset:2560
	ds_read_b128 v[150:153], v230 offset:2576
	ds_read_b128 v[122:125], v230 offset:5120
	ds_read_b128 v[126:129], v230 offset:5136
	ds_read_b128 v[166:169], v230 offset:7696
	v_cvt_pk_fp8_f32 v170, v66, v67
	v_cvt_pk_fp8_f32 v171, v70, v71
	v_cvt_pk_fp8_f32 v172, v74, v75
	v_cvt_pk_fp8_f32 v173, v78, v79
	v_cvt_pk_fp8_f32 v174, v240, v242
	v_cvt_pk_fp8_f32 v175, v245, v246
	v_cvt_pk_fp8_f32 v176, v247, v250
	v_cvt_pk_fp8_f32 v177, v191, v217
	v_cvt_pk_fp8_f32 v170, v68, v69 op_sel:[0,0,1]
	v_cvt_pk_fp8_f32 v171, v72, v73 op_sel:[0,0,1]
	v_cvt_pk_fp8_f32 v172, v76, v77 op_sel:[0,0,1]
	v_cvt_pk_fp8_f32 v173, v80, v81 op_sel:[0,0,1]
	v_cvt_pk_fp8_f32 v174, v239, v241 op_sel:[0,0,1]
	v_cvt_pk_fp8_f32 v175, v243, v244 op_sel:[0,0,1]
	v_cvt_pk_fp8_f32 v176, v248, v249 op_sel:[0,0,1]
	v_cvt_pk_fp8_f32 v177, v251, v252 op_sel:[0,0,1]
	v_max_f32_e32 v0, v83, v83
	v_max_f32_e32 v163, v98, v98
	v_max_f32_e32 v162, v82, v82
	v_max3_f32 v163, v163, v99, v100
	v_max_f32_e32 v0, v162, v0
	v_max3_f32 v163, v163, v101, v102
	v_max3_f32 v0, v0, v84, v85
	v_max3_f32 v163, v163, v103, v104
	v_max3_f32 v0, v0, v86, v87
	v_max3_f32 v163, v163, v105, v106
	v_max3_f32 v0, v0, v88, v89
	v_max3_f32 v163, v163, v107, v108
	v_max3_f32 v0, v0, v90, v91
	v_max3_f32 v163, v163, v109, v110
	v_max3_f32 v0, v0, v92, v93
	v_max3_f32 v163, v163, v111, v112
	v_max3_f32 v0, v0, v94, v95
	v_max_f32_e32 v163, v163, v113
	v_max3_f32 v0, v0, v96, v97
	v_max_f32_e32 v0, v0, v163
	v_mov_b32_e32 v162, v0
	s_nop 1
	v_permlane32_swap_b32_e32 v0, v162
	v_max_f32_e32 v162, v162, v162
	v_max_f32_e32 v0, v0, v0
	v_max_f32_e32 v0, v0, v162
	v_sub_f32_e32 v162, v0, v237
	v_mul_f32_e32 v162, 0x3dd53b94, v162
	v_cmp_ge_f32_e32 vcc, s57, v162
	s_cmp_eq_u64 vcc, exec
	v_max_f32_e32 v162, v237, v237
	s_cselect_b64 vcc, -1, 0
	v_max_f32_e32 v0, v162, v0
	v_cndmask_b32_e32 v238, v0, v237, vcc
	v_sub_f32_e32 v0, v237, v238
	v_mul_f32_e32 v0, 0x3dd53b94, v0
	v_exp_f32_e32 v0, v0
	ds_read_b128 v[162:165], v230 offset:7680
	s_waitcnt lgkmcnt(0)
; #define SBAR() __builtin_amdgcn_sched_barrier(0)
; #define PVC(voff) do { if constexpr (MODE == 0) pv8(o, V_lds + (voff), pa0, pa1, r32, hi); else pv_d0(o, vb0 + (voff), pa0, pa1, pa2, pa3); } while (0)
; #define FSM(P0, P1, AL) do { if constexpr (MODE == 0) finishSM8(P0, P1, AL, l_reg, pa0, pa1); else finishSM(P0, P1, AL, l_reg, pa0, pa1, pa2, pa3); } while (0)
; #define SWAIT() do { if constexpr (SD == 1) asm volatile("s_waitcnt vmcnt(0)" ::: "memory"); else if constexpr (MODE == 0) asm volatile("s_waitcnt vmcnt(5)" ::: "memory"); else asm volatile("s_waitcnt vmcnt(4)" ::: "memory"); } while (0)
; #define SG_QKT() do { if (SGQ) { __builtin_amdgcn_sched_group_barrier(0x100, SGQ_PRE, 0); if constexpr (MODE == 0) { _Pragma("unroll") for (int _g = 0; _g < 6; ++_g) SG_ONE(2, 12, 3); } else { _Pragma("unroll") for (int _g = 0; _g < 16; ++_g) SG_ONE(1, 5, 1); } } } while (0)
; #define SG_PV() do { if (SGP) { __builtin_amdgcn_sched_group_barrier(0x100, SGP_PRE, 0); if constexpr (MODE == 0) { _Pragma("unroll") for (int _g = 0; _g < 4; ++_g) SG_ONE(2, 24, 4); } else { _Pragma("unroll") for (int _g = 0; _g < 16; ++_g) SG_ONE(2, 6, 1); } } } while (0)
; #define RESC(a) do { if (__any((a) < 1.f)) { if (hi == 0) al_l[r32] = (a); asm volatile("s_waitcnt lgkmcnt(0)" ::: "memory"); \
;     _Pragma("unroll") for (int d = 0; d < 4; ++d) _Pragma("unroll") for (int r = 0; r < 16; ++r) o[d][r] *= al_l[crow(r, hi)]; } } while (0)
; template <int MODE, int SD> ...
;     ...
;     SBAR(); qkt<MODE>(pB0, pB1, K_lds + SHM_K, Kr_lds + SHM_KR, Qr_l, qr, q8, r32, hi);
;     FSM(pA0, pA1, alA); SG_QKT(); SBAR();
;     SLOAD(SO, (j + SD) * KVBLK); SBAR();
;     PVC(0); partialSM<MODE>(pB0, pB1, m_reg, mnB, alB, C, kbl + j * KVBLK, btab, nomask); asm volatile("" : "+v"(pB0), "+v"(pB1), "+v"(alB)); SG_PV(); SBAR();
;     __syncthreads(); SWAIT(); SWRITE(0, SE);
;     RESC(alB); __syncthreads();
;     SBAR(); qkt<MODE>(pA0, pA1, K_lds, Kr_lds, Qr_l, qr, q8, r32, hi);
;     FSM(pB0, pB1, alB); SG_QKT(); SBAR();
;     if (SD == 1 || j + 3 < NT) SLOAD(SE, (j + 1 + SD) * KVBLK); SBAR();
;     PVC(SHM_V); partialSM<MODE>(pA0, pA1, m_reg, mnA, alA, C, kbl + (j + 1) * KVBLK, btab, nomask); asm volatile("" : "+v"(pA0), "+v"(pA1), "+v"(alA)); SG_PV(); SBAR();
;     __syncthreads(); SWAIT(); SWRITE(1, SO);
;     RESC(alA); __syncthreads();
	v_mul_f32_e32 v66, 0xbdd53b94, v238
	v_cmp_gt_f32_e32 vcc, 1.0, v0
	s_nop 0
	v_mfma_scale_f32_32x32x64_f8f6f4 v[50:65], v[170:177], v[154:161], v[50:65], v216, v216 op_sel_hi:[0,0,0]
	v_fmamk_f32 v82, v82, 0x3dd53b94, v66
	v_exp_f32_e32 v82, v82
	v_fmamk_f32 v83, v83, 0x3dd53b94, v66
	v_exp_f32_e32 v83, v83
	v_fmamk_f32 v84, v84, 0x3dd53b94, v66
	v_exp_f32_e32 v84, v84
	v_fmamk_f32 v85, v85, 0x3dd53b94, v66
	v_exp_f32_e32 v85, v85
	v_mfma_scale_f32_32x32x64_f8f6f4 v[34:49], v[170:177], v[146:153], v[34:49], v216, v216 op_sel_hi:[0,0,0]
	v_fmamk_f32 v86, v86, 0x3dd53b94, v66
	v_exp_f32_e32 v86, v86
	v_fmamk_f32 v87, v87, 0x3dd53b94, v66
	v_exp_f32_e32 v87, v87
	v_fmamk_f32 v88, v88, 0x3dd53b94, v66
	v_exp_f32_e32 v88, v88
	v_fmamk_f32 v89, v89, 0x3dd53b94, v66
	v_exp_f32_e32 v89, v89
	v_mfma_scale_f32_32x32x64_f8f6f4 v[18:33], v[170:177], v[122:129], v[18:33], v216, v216 op_sel_hi:[0,0,0]
	v_fmamk_f32 v90, v90, 0x3dd53b94, v66
	v_exp_f32_e32 v90, v90
	v_fmamk_f32 v91, v91, 0x3dd53b94, v66
	v_exp_f32_e32 v91, v91
	v_fmamk_f32 v92, v92, 0x3dd53b94, v66
	v_exp_f32_e32 v92, v92
	v_fmamk_f32 v93, v93, 0x3dd53b94, v66
	v_exp_f32_e32 v93, v93
	v_mfma_scale_f32_32x32x64_f8f6f4 v[2:17], v[170:177], v[162:169], v[2:17], v216, v216 op_sel_hi:[0,0,0]
	v_fmamk_f32 v94, v94, 0x3dd53b94, v66
	v_exp_f32_e32 v94, v94
	v_fmamk_f32 v95, v95, 0x3dd53b94, v66
	v_exp_f32_e32 v95, v95
	v_fmamk_f32 v96, v96, 0x3dd53b94, v66
	v_exp_f32_e32 v96, v96
	v_fmamk_f32 v97, v97, 0x3dd53b94, v66
	v_exp_f32_e32 v97, v97
	v_pk_fma_f32 v[98:99], v[98:99], s[78:79], v[66:67] op_sel_hi:[1,0,0]
	v_pk_fma_f32 v[100:101], v[100:101], s[78:79], v[66:67] op_sel_hi:[1,0,0]
	v_pk_fma_f32 v[102:103], v[102:103], s[78:79], v[66:67] op_sel_hi:[1,0,0]
	v_pk_fma_f32 v[104:105], v[104:105], s[78:79], v[66:67] op_sel_hi:[1,0,0]
	v_pk_fma_f32 v[106:107], v[106:107], s[78:79], v[66:67] op_sel_hi:[1,0,0]
	v_pk_fma_f32 v[108:109], v[108:109], s[78:79], v[66:67] op_sel_hi:[1,0,0]
	v_pk_fma_f32 v[110:111], v[110:111], s[78:79], v[66:67] op_sel_hi:[1,0,0]
	v_pk_fma_f32 v[112:113], v[112:113], s[78:79], v[66:67] op_sel_hi:[1,0,0]
	s_cbranch_vccz .LBB0_671
	s_and_saveexec_b64 s[20:21], s[8:9]
	ds_write_b32 v229, v0 offset:128
	s_or_b64 exec, exec, s[20:21]
	s_waitcnt lgkmcnt(0)
	ds_read_b128 v[66:69], v228 offset:224
	ds_read_b128 v[70:73], v228 offset:192
	ds_read_b128 v[74:77], v228 offset:160
	ds_read_b128 v[78:81], v228 offset:128
	s_waitcnt lgkmcnt(3)
	s_nop 7
	v_pk_mul_f32 v[64:65], v[64:65], v[68:69]
	s_waitcnt lgkmcnt(2)
	v_pk_mul_f32 v[60:61], v[60:61], v[72:73]
	s_waitcnt lgkmcnt(1)
	v_pk_mul_f32 v[56:57], v[56:57], v[76:77]
	s_waitcnt lgkmcnt(0)
	v_pk_mul_f32 v[52:53], v[52:53], v[80:81]
	v_pk_mul_f32 v[62:63], v[62:63], v[66:67]
	v_pk_mul_f32 v[58:59], v[58:59], v[70:71]
	v_pk_mul_f32 v[54:55], v[54:55], v[74:75]
	v_pk_mul_f32 v[50:51], v[50:51], v[78:79]
	v_pk_mul_f32 v[48:49], v[48:49], v[68:69]
	v_pk_mul_f32 v[44:45], v[44:45], v[72:73]
	v_pk_mul_f32 v[40:41], v[40:41], v[76:77]
	v_pk_mul_f32 v[36:37], v[36:37], v[80:81]
	v_pk_mul_f32 v[46:47], v[46:47], v[66:67]
	v_pk_mul_f32 v[42:43], v[42:43], v[70:71]
	v_pk_mul_f32 v[38:39], v[38:39], v[74:75]
	v_pk_mul_f32 v[34:35], v[34:35], v[78:79]
	v_pk_mul_f32 v[32:33], v[32:33], v[68:69]
	v_pk_mul_f32 v[28:29], v[28:29], v[72:73]
	v_pk_mul_f32 v[24:25], v[24:25], v[76:77]
	v_pk_mul_f32 v[20:21], v[20:21], v[80:81]
	v_pk_mul_f32 v[30:31], v[30:31], v[66:67]
	v_pk_mul_f32 v[26:27], v[26:27], v[70:71]
	v_pk_mul_f32 v[22:23], v[22:23], v[74:75]
	v_pk_mul_f32 v[18:19], v[18:19], v[78:79]
	v_pk_mul_f32 v[16:17], v[16:17], v[68:69]
	v_pk_mul_f32 v[12:13], v[12:13], v[72:73]
	v_pk_mul_f32 v[8:9], v[8:9], v[76:77]
	v_pk_mul_f32 v[4:5], v[4:5], v[80:81]
	v_pk_mul_f32 v[14:15], v[14:15], v[66:67]
	v_pk_mul_f32 v[10:11], v[10:11], v[70:71]
	v_pk_mul_f32 v[6:7], v[6:7], v[74:75]
	v_pk_mul_f32 v[2:3], v[2:3], v[78:79]
.LBB0_671:
	s_waitcnt vmcnt(0)
	s_waitcnt vmcnt(1)
	ds_write_b128 v225, v[182:185]
	s_waitcnt vmcnt(0)
	ds_write_b128 v226, v[186:189] offset:32768
	s_and_saveexec_b64 s[20:21], s[12:13]
	ds_write_b128 v234, v[178:181] offset:32768
	s_or_b64 exec, exec, s[20:21]
	s_lshl_b32 s26, s25, 6
	s_waitcnt lgkmcnt(0)
	s_barrier
	ds_read_b128 v[66:69], v231 offset:32768
	ds_read_b128 v[70:73], v231 offset:32784
	ds_read_b128 v[122:125], v231 offset:32832
	ds_read_b128 v[126:129], v231 offset:32848
	ds_read_b128 v[162:165], v231 offset:32896
	ds_read_b128 v[166:169], v231 offset:32912
	ds_read_b128 v[146:149], v231 offset:39424
	ds_read_b128 v[150:153], v231 offset:39440
	ds_read_b128 v[154:157], v231 offset:39488
	ds_read_b128 v[158:161], v231 offset:39504
	ds_read_b128 v[170:173], v231 offset:39552
	ds_read_b128 v[174:177], v231 offset:39568
	global_load_dwordx4 v[182:185], v[208:209], off offset:64
	global_load_dwordx4 v[186:189], v[206:207], off
	s_and_saveexec_b64 s[20:21], s[12:13]
	global_load_dwordx4 v[178:181], v[204:205], off
	s_or_b64 exec, exec, s[20:21]
	v_lshl_add_u64 v[206:207], v[206:207], 0, v[212:213]
	v_lshl_add_u64 v[204:205], v[204:205], 0, v[210:211]
	s_waitcnt lgkmcnt(10)
	v_mfma_scale_f32_32x32x64_f8f6f4 v[66:81], v[66:73], v[114:121], 0, v216, v216 op_sel_hi:[0,0,0]
	v_exp_f32_e32 v243, v98
	v_exp_f32_e32 v244, v99
	v_exp_f32_e32 v241, v100
	v_exp_f32_e32 v242, v101
	v_exp_f32_e32 v247, v102
	v_exp_f32_e32 v248, v103
	v_add_f32_e32 v239, 0, v82
	v_add_f32_e32 v239, v83, v239
	s_waitcnt lgkmcnt(8)
	v_mfma_scale_f32_32x32x64_f8f6f4 v[66:81], v[122:129], v[130:137], v[66:81], v216, v216 op_sel_hi:[0,0,0]
	v_exp_f32_e32 v245, v104
	v_exp_f32_e32 v246, v105
	v_exp_f32_e32 v249, v106
	v_exp_f32_e32 v252, v107
	v_exp_f32_e32 v250, v108
	v_exp_f32_e32 v251, v109
	v_add_f32_e32 v239, v84, v239
	v_add_f32_e32 v239, v85, v239
	s_waitcnt lgkmcnt(6)
; __device__ __forceinline__ unsigned pk4_fp8(float a, float b, float c, float d) { int p = __builtin_amdgcn_cvt_pk_fp8_f32(a, b, 0, false); p = __builtin_amdgcn_cvt_pk_fp8_f32(c, d, p, true); return (unsigned)p; }
; template <int MODE>
; __device__ __forceinline__ void partialSM(f32x16& p0, f32x16& p1, float& m_reg, float& mn, float& alpha, const float C, int kb, const float* btab, const bool nomask) {
;     ...
;     float pmax = p0[0];
; #pragma unroll
;     for (int r = 1; r < 16; ++r) pmax = fmaxf(pmax, p0[r]);
; #pragma unroll
;     for (int r = 0; r < 16; ++r) pmax = fmaxf(pmax, p1[r]);
;     { auto rr = __builtin_amdgcn_permlane32_swap(__float_as_uint(pmax), __float_as_uint(pmax), false, false); pmax = fmaxf(__uint_as_float(rr[0]), __uint_as_float(rr[1])); }
;     { const bool keep = __all((pmax - m_reg) * C <= (MODE == 0 ? 7.5f : 11.5f)); mn = keep ? m_reg : fmaxf(m_reg, pmax);   alpha = __builtin_amdgcn_exp2f((m_reg - mn) * C); m_reg = mn; }
; __device__ __forceinline__ void finishSM8(f32x16& p0, f32x16& p1, float alpha, float& l_reg, bf16x8& pa0, bf16x8& pa1) {
;     ...
;   const u32x4 w0 = {pk4_fp8(p0[0], p0[1], p0[2], p0[3]), pk4_fp8(p0[4], p0[5], p0[6], p0[7]), pk4_fp8(p0[8], p0[9], p0[10], p0[11]), pk4_fp8(p0[12], p0[13], p0[14], p0[15])};
;   const u32x4 w1 = {pk4_fp8(p1[0], p1[1], p1[2], p1[3]), pk4_fp8(p1[4], p1[5], p1[6], p1[7]), pk4_fp8(p1[8], p1[9], p1[10], p1[11]), pk4_fp8(p1[12], p1[13], p1[14], p1[15])};
;   pa0 = __builtin_bit_cast(bf16x8, w0); pa1 = __builtin_bit_cast(bf16x8, w1);
; }
; __device__ __forceinline__ void pv8(f32x16* o, const char* Vs, bf16x8 pa0, bf16x8 pa1, int r32, int hi) {
;   const u32x4 a0 = __builtin_bit_cast(u32x4, pa0), a1 = __builtin_bit_cast(u32x4, pa1);
;   const i32x8 P = {(int)a0.x, (int)a0.y, (int)a0.z, (int)a0.w, (int)a1.x, (int)a1.y, (int)a1.z, (int)a1.w};
; #pragma unroll
;   for (int d0 = 0; d0 < 4; ++d0) { const char* b_ = Vs + (d0 * 32 + r32) * 80 + hi * 32;
;     const u32x4 lo = *reinterpret_cast<const u32x4*>(b_), h4 = *reinterpret_cast<const u32x4*>(b_ + 16);
;     const i32x8 V = {(int)lo.x, (int)lo.y, (int)lo.z, (int)lo.w, (int)h4.x, (int)h4.y, (int)h4.z, (int)h4.w};
;     o[d0] = __builtin_amdgcn_mfma_scale_f32_32x32x64_f8f6f4(P, V, o[d0], 0, 0, 0, 0x7F7F7F7F, 0, 0x7F7F7F7F); }
	v_mfma_scale_f32_32x32x64_f8f6f4 v[66:81], v[162:169], v[138:145], v[66:81], v216, v216 op_sel_hi:[0,0,0]
	v_exp_f32_e32 v254, v110
	v_exp_f32_e32 v191, v111
	v_exp_f32_e32 v253, v112
	v_exp_f32_e32 v217, v113
	v_add_f32_e32 v239, v86, v239
	v_add_f32_e32 v239, v87, v239
	v_add_f32_e32 v239, v88, v239
	v_add_f32_e32 v239, v89, v239
	v_add_f32_e32 v239, v90, v239
	v_add_f32_e32 v239, v91, v239
	s_waitcnt lgkmcnt(4)
	v_mfma_scale_f32_32x32x64_f8f6f4 v[98:113], v[146:153], v[114:121], 0, v216, v216 op_sel_hi:[0,0,0]
	v_add_f32_e32 v239, v92, v239
	v_add_f32_e32 v239, v93, v239
	v_add_f32_e32 v239, v94, v239
	v_add_f32_e32 v239, v95, v239
	v_add_f32_e32 v239, v96, v239
	v_add_f32_e32 v239, v97, v239
	v_add_f32_e32 v239, v243, v239
	v_add_f32_e32 v239, v244, v239
	v_add_f32_e32 v239, v241, v239
	v_add_f32_e32 v239, v242, v239
	v_add_f32_e32 v239, v247, v239
	s_waitcnt lgkmcnt(2)
	v_mfma_scale_f32_32x32x64_f8f6f4 v[98:113], v[154:161], v[130:137], v[98:113], v216, v216 op_sel_hi:[0,0,0]
	v_add_f32_e32 v239, v248, v239
	v_add_f32_e32 v239, v245, v239
	v_add_f32_e32 v239, v246, v239
	v_add_f32_e32 v239, v249, v239
	v_add_f32_e32 v239, v252, v239
	v_add_f32_e32 v239, v250, v239
	v_add_f32_e32 v239, v251, v239
	v_add_f32_e32 v239, v254, v239
	v_add_f32_e32 v239, v191, v239
	v_add_f32_e32 v239, v253, v239
	s_waitcnt lgkmcnt(0)
	v_mfma_scale_f32_32x32x64_f8f6f4 v[98:113], v[170:177], v[138:145], v[98:113], v216, v216 op_sel_hi:[0,0,0]
	s_nop 0
	v_add_f32_e32 v239, v217, v239
	v_mov_b32_e32 v240, v239
	s_nop 1
	v_permlane32_swap_b32_e32 v239, v240
	ds_read_b128 v[154:157], v230 offset:18432
	ds_read_b128 v[158:161], v230 offset:18448
	ds_read_b128 v[146:149], v230 offset:20992
	ds_read_b128 v[150:153], v230 offset:21008
	ds_read_b128 v[122:125], v230 offset:23552
	ds_read_b128 v[126:129], v230 offset:23568
	ds_read_b128 v[166:169], v230 offset:26128
	v_cvt_pk_fp8_f32 v82, v82, v83
	v_cvt_pk_fp8_f32 v83, v86, v87
	v_cvt_pk_fp8_f32 v82, v84, v85 op_sel:[0,0,1]
	v_cvt_pk_fp8_f32 v83, v88, v89 op_sel:[0,0,1]
	v_cvt_pk_fp8_f32 v84, v90, v91
	v_cvt_pk_fp8_f32 v85, v94, v95
	v_cvt_pk_fp8_f32 v84, v92, v93 op_sel:[0,0,1]
	v_cvt_pk_fp8_f32 v85, v96, v97 op_sel:[0,0,1]
	v_cvt_pk_fp8_f32 v86, v243, v244
	v_cvt_pk_fp8_f32 v87, v247, v248
	v_cvt_pk_fp8_f32 v86, v241, v242 op_sel:[0,0,1]
	v_cvt_pk_fp8_f32 v87, v245, v246 op_sel:[0,0,1]
	v_cvt_pk_fp8_f32 v88, v249, v252
	v_cvt_pk_fp8_f32 v89, v254, v191
	v_cvt_pk_fp8_f32 v88, v250, v251 op_sel:[0,0,1]
	v_cvt_pk_fp8_f32 v89, v253, v217 op_sel:[0,0,1]
	v_max_f32_e32 v162, v67, v67
	v_max_f32_e32 v164, v98, v98
	v_max_f32_e32 v163, v66, v66
	v_max3_f32 v164, v164, v99, v100
	v_max_f32_e32 v162, v163, v162
	v_max3_f32 v164, v164, v101, v102
	v_max3_f32 v162, v162, v68, v69
	v_max3_f32 v164, v164, v103, v104
	v_max3_f32 v162, v162, v70, v71
	v_max3_f32 v164, v164, v105, v106
	v_max3_f32 v162, v162, v72, v73
	v_max3_f32 v164, v164, v107, v108
	v_max3_f32 v162, v162, v74, v75
	v_max3_f32 v164, v164, v109, v110
	v_max3_f32 v162, v162, v76, v77
	v_max3_f32 v164, v164, v111, v112
	v_max3_f32 v162, v162, v78, v79
	v_max_f32_e32 v164, v164, v113
	v_max3_f32 v162, v162, v80, v81
	v_max_f32_e32 v162, v162, v164
	v_mov_b32_e32 v163, v162
	s_nop 1
	v_permlane32_swap_b32_e32 v162, v163
	v_max_f32_e32 v163, v163, v163
	v_max_f32_e32 v162, v162, v162
	v_max_f32_e32 v162, v162, v163
	v_sub_f32_e32 v163, v162, v238
	v_mul_f32_e32 v163, 0x3dd53b94, v163
	v_cmp_ge_f32_e32 vcc, s57, v163
	s_cmp_eq_u64 vcc, exec
	v_max_f32_e32 v163, v238, v238
	s_cselect_b64 vcc, -1, 0
	v_max_f32_e32 v162, v163, v162
	v_cndmask_b32_e32 v237, v162, v238, vcc
	v_sub_f32_e32 v170, v238, v237
	v_mul_f32_e32 v170, 0x3dd53b94, v170
	v_exp_f32_e32 v170, v170
	ds_read_b128 v[162:165], v230 offset:26112
	s_waitcnt lgkmcnt(0)
	v_mul_f32_e32 v172, 0xbdd53b94, v237
	v_cmp_gt_f32_e32 vcc, 1.0, v170
	s_nop 0
	v_mfma_scale_f32_32x32x64_f8f6f4 v[50:65], v[82:89], v[154:161], v[50:65], v216, v216 op_sel_hi:[0,0,0]
	v_fmamk_f32 v66, v66, 0x3dd53b94, v172
	v_exp_f32_e32 v66, v66
	v_fmamk_f32 v67, v67, 0x3dd53b94, v172
	v_exp_f32_e32 v67, v67
	v_fmamk_f32 v68, v68, 0x3dd53b94, v172
	v_exp_f32_e32 v68, v68
	v_fmamk_f32 v69, v69, 0x3dd53b94, v172
	v_exp_f32_e32 v69, v69
	v_mfma_scale_f32_32x32x64_f8f6f4 v[34:49], v[82:89], v[146:153], v[34:49], v216, v216 op_sel_hi:[0,0,0]
	v_fmamk_f32 v70, v70, 0x3dd53b94, v172
	v_exp_f32_e32 v70, v70
	v_fmamk_f32 v71, v71, 0x3dd53b94, v172
	v_exp_f32_e32 v71, v71
	v_fmamk_f32 v72, v72, 0x3dd53b94, v172
	v_exp_f32_e32 v72, v72
	v_fmamk_f32 v73, v73, 0x3dd53b94, v172
	v_exp_f32_e32 v73, v73
	v_mfma_scale_f32_32x32x64_f8f6f4 v[18:33], v[82:89], v[122:129], v[18:33], v216, v216 op_sel_hi:[0,0,0]
	v_fmamk_f32 v74, v74, 0x3dd53b94, v172
	v_exp_f32_e32 v74, v74
	v_fmamk_f32 v75, v75, 0x3dd53b94, v172
	v_exp_f32_e32 v75, v75
	v_fmamk_f32 v76, v76, 0x3dd53b94, v172
	v_exp_f32_e32 v76, v76
	v_fmamk_f32 v77, v77, 0x3dd53b94, v172
	v_exp_f32_e32 v77, v77
	v_mfma_scale_f32_32x32x64_f8f6f4 v[2:17], v[82:89], v[162:169], v[2:17], v216, v216 op_sel_hi:[0,0,0]
	v_fmamk_f32 v78, v78, 0x3dd53b94, v172
	v_exp_f32_e32 v78, v78
	v_fmamk_f32 v79, v79, 0x3dd53b94, v172
	v_exp_f32_e32 v79, v79
	v_fmamk_f32 v80, v80, 0x3dd53b94, v172
	v_exp_f32_e32 v80, v80
	v_fmamk_f32 v81, v81, 0x3dd53b94, v172
	v_exp_f32_e32 v81, v81
	v_pk_fma_f32 v[98:99], v[98:99], s[78:79], v[172:173] op_sel_hi:[1,0,0]
	v_pk_fma_f32 v[100:101], v[100:101], s[78:79], v[172:173] op_sel_hi:[1,0,0]
	v_pk_fma_f32 v[102:103], v[102:103], s[78:79], v[172:173] op_sel_hi:[1,0,0]
	v_pk_fma_f32 v[104:105], v[104:105], s[78:79], v[172:173] op_sel_hi:[1,0,0]
	v_pk_fma_f32 v[106:107], v[106:107], s[78:79], v[172:173] op_sel_hi:[1,0,0]
	v_pk_fma_f32 v[108:109], v[108:109], s[78:79], v[172:173] op_sel_hi:[1,0,0]
	v_pk_fma_f32 v[110:111], v[110:111], s[78:79], v[172:173] op_sel_hi:[1,0,0]
	v_pk_fma_f32 v[112:113], v[112:113], s[78:79], v[172:173] op_sel_hi:[1,0,0]
	s_cbranch_vccz .LBB0_654
	s_and_saveexec_b64 s[20:21], s[8:9]
	s_cbranch_execz .LBB0_653
	ds_write_b32 v229, v170 offset:128
	s_branch .LBB0_653

; #define SBAR() __builtin_amdgcn_sched_barrier(0)
; #define PVC(voff) do { if constexpr (MODE == 0) pv8(o, V_lds + (voff), pa0, pa1, r32, hi); else pv_d0(o, vb0 + (voff), pa0, pa1, pa2, pa3); } while (0)
; #define FSM(P0, P1, AL) do { if constexpr (MODE == 0) finishSM8(P0, P1, AL, l_reg, pa0, pa1); else finishSM(P0, P1, AL, l_reg, pa0, pa1, pa2, pa3); } while (0)
; #define RESC(a) do { if (__any((a) < 1.f)) { if (hi == 0) al_l[r32] = (a); asm volatile("s_waitcnt lgkmcnt(0)" ::: "memory"); \
;     _Pragma("unroll") for (int d = 0; d < 4; ++d) _Pragma("unroll") for (int r = 0; r < 16; ++r) o[d][r] *= al_l[crow(r, hi)]; } } while (0)
; __device__ __forceinline__ void finishSM8(f32x16& p0, f32x16& p1, float alpha, float& l_reg, bf16x8& pa0, bf16x8& pa1) {
; #pragma unroll
;   for (int r = 0; r < 16; ++r) p1[r] = __builtin_amdgcn_exp2f(p1[r]);
;   float ps = 0;
; #pragma unroll
;   for (int r = 0; r < 16; ++r) ps += p0[r];
; #pragma unroll
;   for (int r = 0; r < 16; ++r) ps += p1[r];
;   { auto rr = __builtin_amdgcn_permlane32_swap(__float_as_uint(ps), __float_as_uint(ps), false, false); ps = __uint_as_float(rr[0]) + __uint_as_float(rr[1]); }
;   l_reg = l_reg * alpha + ps;
; template <int MODE, int SD> ...
;     ...
;   SBAR(); qkt<MODE>(pB0, pB1, K_lds + SHM_K, Kr_lds + SHM_KR, Qr_l, qr, q8, r32, hi);
;   FSM(pA0, pA1, alA); SBAR();
;   PVC(0); partialSM<MODE>(pB0, pB1, m_reg, mnB, alB, C, kbl + (NT - 1) * KVBLK, btab, nomask);
;   __syncthreads(); RESC(alB);
;   FSM(pB0, pB1, alB); SBAR();
;   PVC(SHM_V);
;   if constexpr (MODE == 1) l_reg += __builtin_amdgcn_exp2f(sink_l2 - m_reg);
;   if (hi == 0) li_l[r32] = l_reg; asm volatile("s_waitcnt lgkmcnt(0)" ::: "memory");
.LBB0_690:
	v_mul_f32_e32 v66, 0xbdd53b94, v66
	v_fmamk_f32 v80, v82, 0x3dd53b94, v66
	v_fmamk_f32 v81, v83, 0x3dd53b94, v66
	v_fmamk_f32 v68, v115, 0x3dd53b94, v66
	v_exp_f32_e32 v115, v80
	v_fmamk_f32 v82, v84, 0x3dd53b94, v66
	v_fmamk_f32 v73, v120, 0x3dd53b94, v66
	v_exp_f32_e32 v120, v81
	v_fmamk_f32 v83, v85, 0x3dd53b94, v66
	v_exp_f32_e32 v100, v82
	v_fmamk_f32 v84, v86, 0x3dd53b94, v66
	v_fmamk_f32 v85, v87, 0x3dd53b94, v66
	v_fmamk_f32 v86, v88, 0x3dd53b94, v66
	v_fmamk_f32 v87, v89, 0x3dd53b94, v66
	v_fmamk_f32 v88, v90, 0x3dd53b94, v66
	v_fmamk_f32 v89, v91, 0x3dd53b94, v66
	v_fmamk_f32 v90, v92, 0x3dd53b94, v66
	v_fmamk_f32 v91, v93, 0x3dd53b94, v66
	v_fmamk_f32 v92, v94, 0x3dd53b94, v66
	v_fmamk_f32 v93, v95, 0x3dd53b94, v66
	v_fmamk_f32 v94, v96, 0x3dd53b94, v66
	v_fmamk_f32 v95, v97, 0x3dd53b94, v66
	v_fmamk_f32 v67, v114, 0x3dd53b94, v66
	v_fmamk_f32 v69, v116, 0x3dd53b94, v66
	v_fmamk_f32 v70, v117, 0x3dd53b94, v66
	v_fmamk_f32 v71, v118, 0x3dd53b94, v66
	v_fmamk_f32 v72, v119, 0x3dd53b94, v66
	v_fmamk_f32 v74, v121, 0x3dd53b94, v66
	v_fmamk_f32 v75, v122, 0x3dd53b94, v66
	v_fmamk_f32 v76, v123, 0x3dd53b94, v66
	v_fmamk_f32 v77, v124, 0x3dd53b94, v66
	v_fmamk_f32 v78, v125, 0x3dd53b94, v66
	v_fmamk_f32 v79, v126, 0x3dd53b94, v66
	v_exp_f32_e32 v101, v83
	v_fmamk_f32 v80, v127, 0x3dd53b94, v66
	v_fmamk_f32 v81, v128, 0x3dd53b94, v66
	v_fmac_f32_e32 v66, 0x3dd53b94, v129
	v_exp_f32_e32 v116, v84
	v_exp_f32_e32 v119, v66
	v_add_f32_e32 v66, 0, v115
	v_exp_f32_e32 v121, v85
	v_add_f32_e32 v66, v120, v66
	v_exp_f32_e32 v103, v86
	v_add_f32_e32 v66, v100, v66
	v_exp_f32_e32 v105, v87
	v_add_f32_e32 v66, v101, v66
	v_exp_f32_e32 v117, v88
	v_add_f32_e32 v66, v116, v66
	v_exp_f32_e32 v122, v89
	v_add_f32_e32 v66, v121, v66
	v_exp_f32_e32 v107, v90
	v_add_f32_e32 v66, v103, v66
	v_exp_f32_e32 v109, v91
	v_add_f32_e32 v66, v105, v66
	v_exp_f32_e32 v118, v92
	v_add_f32_e32 v66, v117, v66
	v_exp_f32_e32 v123, v93
	v_add_f32_e32 v66, v122, v66
	v_exp_f32_e32 v110, v94
	v_add_f32_e32 v66, v107, v66
	v_exp_f32_e32 v112, v95
	v_add_f32_e32 v66, v109, v66
	v_exp_f32_e32 v124, v67
	v_add_f32_e32 v66, v118, v66
	v_exp_f32_e32 v128, v68
	v_add_f32_e32 v66, v123, v66
	v_exp_f32_e32 v102, v69
	v_add_f32_e32 v66, v110, v66
	v_exp_f32_e32 v104, v70
	v_add_f32_e32 v66, v112, v66
	v_exp_f32_e32 v125, v71
	v_add_f32_e32 v66, v124, v66
	v_exp_f32_e32 v129, v72
	v_add_f32_e32 v66, v128, v66
	v_exp_f32_e32 v106, v73
	v_add_f32_e32 v66, v102, v66
	v_exp_f32_e32 v108, v74
	v_add_f32_e32 v66, v104, v66
	v_exp_f32_e32 v126, v75
	v_add_f32_e32 v66, v125, v66
	v_exp_f32_e32 v130, v76
	v_add_f32_e32 v66, v129, v66
	v_exp_f32_e32 v111, v77
	v_add_f32_e32 v66, v106, v66
	v_exp_f32_e32 v113, v78
	v_add_f32_e32 v66, v108, v66
	v_exp_f32_e32 v127, v79
	v_add_f32_e32 v66, v126, v66
	v_exp_f32_e32 v131, v80
	v_add_f32_e32 v66, v130, v66
	v_exp_f32_e32 v114, v81
	v_add_f32_e32 v66, v111, v66
	v_add_f32_e32 v66, v113, v66
	v_add_f32_e32 v66, v127, v66
	v_add_f32_e32 v66, v131, v66
	v_add_f32_e32 v66, v114, v66
	v_add_f32_e32 v132, v119, v66
	v_mov_b32_e32 v133, v132
	s_nop 1
	v_permlane32_swap_b32_e32 v132, v133
	ds_read_b128 v[90:93], v230 offset:18432
	ds_read_b128 v[94:97], v230 offset:18448
	ds_read_b128 v[82:85], v230 offset:20992
	ds_read_b128 v[86:89], v230 offset:21008
	ds_read_b128 v[74:77], v230 offset:23552
	ds_read_b128 v[78:81], v230 offset:23568
	ds_read_b128 v[66:69], v230 offset:26112
	ds_read_b128 v[70:73], v230 offset:26128
	s_and_saveexec_b64 s[10:11], s[8:9]
	s_cbranch_execz .LBB0_451
	v_add_f32_e32 v0, v0, v98
	v_fmac_f32_e32 v0, v193, v170
	v_add_f32_e32 v98, v132, v133
	v_fmac_f32_e32 v98, v0, v99
	ds_write_b32 v229, v98
	s_branch .LBB0_451
